# barrier B6: cache invalidates moved off the release path (members invalidate once their XCD has fully arrived, leaders before their spin) + peel + packed SwiGLU
# speedup vs baseline: 1.0031x; 1.0031x over previous
.LBB0_115:
	s_lshl_b32 s2, s86, 8
	s_add_u32 s4, s84, s2
	s_addc_u32 s5, s85, 0
	v_mov_b32_e32 v3, 0x1000
	v_mov_b32_e32 v5, 1
	global_atomic_add v5, v3, v5, s[4:5] offset:1024 sc0
	v_cvt_f32_u32_e32 v3, v4
	v_sub_u32_e32 v6, 0, v4
	v_rcp_iflag_f32_e32 v3, v3
	s_nop 0
	v_mul_f32_e32 v3, 0x4f7ffffe, v3
	v_cvt_u32_f32_e32 v3, v3
	v_mul_lo_u32 v6, v6, v3
	v_mul_hi_u32 v6, v3, v6
	v_add_u32_e32 v3, v3, v6
	s_waitcnt vmcnt(0)
	v_mul_hi_u32 v3, v5, v3
	v_mul_lo_u32 v6, v3, v4
	v_sub_u32_e32 v6, v5, v6
	v_add_u32_e32 v7, 1, v3
	v_cmp_ge_u32_e32 vcc, v6, v4
	v_add_u32_e32 v5, 1, v5
	s_nop 0
	v_cndmask_b32_e32 v3, v3, v7, vcc
	v_sub_u32_e32 v7, v6, v4
	v_cndmask_b32_e32 v6, v6, v7, vcc
	v_add_u32_e32 v7, 1, v3
	v_cmp_ge_u32_e32 vcc, v6, v4
	s_nop 1
	v_cndmask_b32_e32 v3, v3, v7, vcc
	v_mul_lo_u32 v6, v4, v3
	v_add_u32_e32 v4, v6, v4
	v_cmp_ne_u32_e32 vcc, v5, v4
	s_and_saveexec_b64 s[2:3], vcc
	s_xor_b64 s[6:7], exec, s[2:3]
	s_cbranch_execz .LBB0_129
	s_waitcnt lgkmcnt(0)
	v_mov_b32_e32 v2, 0x2000
	global_load_dword v2, v2, s[4:5] offset:1024 sc1
	s_add_u32 s18, s4, 0x2400
	s_addc_u32 s19, s5, 0
	s_waitcnt vmcnt(0)
	v_cmp_eq_u32_e32 vcc, v2, v3
	s_and_saveexec_b64 s[12:13], vcc
	s_cbranch_execz .LBB0_128
	v_mov_b32_e32 v2, 0
	v_mov_b32_e32 v4, 0x1400
	s_mov_b32 s2, 0
	s_mov_b32 s3, 0
.Lb6l_0:
	s_sleep 1
	global_load_dword v17, v2, s[18:19] sc1
	s_cmp_lg_u32 s2, 0
	s_cbranch_scc1 .Lb6b_0
	global_load_dword v18, v4, s[4:5] offset:128 sc1
	s_waitcnt vmcnt(0)
	v_cmp_ne_u32_e32 vcc, v17, v3
	s_cbranch_vccnz .LBB0_128
	v_cmp_le_u32_e32 vcc, v18, v3
	s_cbranch_vccnz .Lb6c_0
	buffer_inv sc1
	s_mov_b32 s2, 1
	s_branch .Lb6c_0
.Lb6b_0:
	s_waitcnt vmcnt(0)
	v_cmp_ne_u32_e32 vcc, v17, v3
	s_cbranch_vccnz .Lb6done_0
.Lb6c_0:
	s_add_u32 s3, s3, 1
	s_cmp_lt_u32 s3, 0x100000
	s_cbranch_scc1 .Lb6l_0
	s_branch .LBB0_128
.Lb6done_0:
	s_waitcnt vmcnt(0)
	s_branch .LBB0_129

.LBB0_129:
	s_andn2_saveexec_b64 s[2:3], s[6:7]
	s_cbranch_execz .LBB0_147
	s_mov_b64 s[6:7], exec
	buffer_wbl2 sc1
	s_waitcnt lgkmcnt(0)
	s_waitcnt vmcnt(0)
	v_mov_b32_e32 v4, 0x1400
	v_mov_b32_e32 v5, 1
	global_atomic_add v4, v5, s[4:5] offset:128
	v_mbcnt_lo_u32_b32 v3, s6, 0
	v_mbcnt_hi_u32_b32 v3, s7, v3
	v_cmp_eq_u32_e32 vcc, 0, v3
	s_and_saveexec_b64 s[12:13], vcc
	s_cbranch_execz .LBB0_132
	s_bcnt1_i32_b64 s2, s[6:7]
	v_mov_b32_e32 v4, 0x7000
	v_mov_b32_e32 v5, s2
	global_atomic_add v4, v4, v5, s[82:83] offset:1024 sc0

.Lb1spin_0:
	buffer_inv sc1
	v_mov_b32_e32 v2, 0
	global_load_dword v3, v2, s[12:13] sc1
	s_mov_b64 s[20:21], 0
	s_waitcnt vmcnt(0)
	v_cmp_eq_u32_e32 vcc, v3, v4
	s_and_saveexec_b64 s[18:19], vcc
	s_cbranch_execz .LBB0_143
	s_add_u32 s16, s82, 0x4200
	s_addc_u32 s17, s83, 0
	s_mov_b32 s2, 1
	s_branch .LBB0_136

.LBB0_146:
	s_or_b64 exec, exec, s[6:7]
	v_mov_b32_e32 v2, 0x2000
	v_mov_b32_e32 v3, 1
	s_waitcnt vmcnt(0)
	s_waitcnt vmcnt(0)

.LBB0_443:
	s_lshl_b32 s2, s86, 8
	s_add_u32 s4, s84, s2
	s_addc_u32 s5, s85, 0
	v_mov_b32_e32 v3, 0x1000
	v_mov_b32_e32 v5, 1
	global_atomic_add v5, v3, v5, s[4:5] offset:1024 sc0
	v_cvt_f32_u32_e32 v3, v4
	v_sub_u32_e32 v6, 0, v4
	v_rcp_iflag_f32_e32 v3, v3
	s_nop 0
	v_mul_f32_e32 v3, 0x4f7ffffe, v3
	v_cvt_u32_f32_e32 v3, v3
	v_mul_lo_u32 v6, v6, v3
	v_mul_hi_u32 v6, v3, v6
	v_add_u32_e32 v3, v3, v6
	s_waitcnt vmcnt(0)
	v_mul_hi_u32 v3, v5, v3
	v_mul_lo_u32 v6, v3, v4
	v_sub_u32_e32 v6, v5, v6
	v_add_u32_e32 v7, 1, v3
	v_cmp_ge_u32_e32 vcc, v6, v4
	v_add_u32_e32 v5, 1, v5
	s_nop 0
	v_cndmask_b32_e32 v3, v3, v7, vcc
	v_sub_u32_e32 v7, v6, v4
	v_cndmask_b32_e32 v6, v6, v7, vcc
	v_add_u32_e32 v7, 1, v3
	v_cmp_ge_u32_e32 vcc, v6, v4
	s_nop 1
	v_cndmask_b32_e32 v3, v3, v7, vcc
	v_mul_lo_u32 v6, v4, v3
	v_add_u32_e32 v4, v6, v4
	v_cmp_ne_u32_e32 vcc, v5, v4
	s_and_saveexec_b64 s[2:3], vcc
	s_xor_b64 s[6:7], exec, s[2:3]
	s_cbranch_execz .LBB0_457
	s_waitcnt lgkmcnt(0)
	v_mov_b32_e32 v2, 0x2000
	global_load_dword v2, v2, s[4:5] offset:1024 sc1
	s_add_u32 s12, s4, 0x2400
	s_addc_u32 s13, s5, 0
	s_waitcnt vmcnt(0)
	v_cmp_eq_u32_e32 vcc, v2, v3
	s_and_saveexec_b64 s[8:9], vcc
	s_cbranch_execz .LBB0_456
	v_mov_b32_e32 v2, 0
	v_mov_b32_e32 v4, 0x1400
	s_mov_b32 s2, 0
	s_mov_b32 s3, 0
.Lb6l_5:
	s_sleep 1
	global_load_dword v17, v2, s[12:13] sc1
	s_cmp_lg_u32 s2, 0
	s_cbranch_scc1 .Lb6b_5
	global_load_dword v18, v4, s[4:5] offset:128 sc1
	s_waitcnt vmcnt(0)
	v_cmp_ne_u32_e32 vcc, v17, v3
	s_cbranch_vccnz .LBB0_456
	v_cmp_le_u32_e32 vcc, v18, v3
	s_cbranch_vccnz .Lb6c_5
	buffer_inv sc1
	s_mov_b32 s2, 1
	s_branch .Lb6c_5

.LBB0_457:
	s_andn2_saveexec_b64 s[2:3], s[6:7]
	s_cbranch_execz .LBB0_475
	s_mov_b64 s[6:7], exec
	buffer_wbl2 sc1
	s_waitcnt lgkmcnt(0)
	s_waitcnt vmcnt(0)
	v_mov_b32_e32 v4, 0x1400
	v_mov_b32_e32 v5, 1
	global_atomic_add v4, v5, s[4:5] offset:128
	v_mbcnt_lo_u32_b32 v3, s6, 0
	v_mbcnt_hi_u32_b32 v3, s7, v3
	v_cmp_eq_u32_e32 vcc, 0, v3
	s_and_saveexec_b64 s[8:9], vcc
	s_cbranch_execz .LBB0_460
	s_bcnt1_i32_b64 s2, s[6:7]
	v_mov_b32_e32 v4, 0x7000
	v_mov_b32_e32 v5, s2
	global_atomic_add v4, v4, v5, s[82:83] offset:1024 sc0

.Lb1spin_5:
	buffer_inv sc1
	v_mov_b32_e32 v2, 0
	global_load_dword v3, v2, s[8:9] sc1
	s_mov_b64 s[16:17], 0
	s_waitcnt vmcnt(0)
	v_cmp_eq_u32_e32 vcc, v3, v4
	s_and_saveexec_b64 s[12:13], vcc
	s_cbranch_execz .LBB0_471
	s_add_u32 s10, s82, 0x4200
	s_addc_u32 s11, s83, 0
	s_mov_b32 s2, 1
	s_branch .LBB0_464

.LBB0_645:
	s_lshl_b32 s2, s86, 8
	s_add_u32 s4, s84, s2
	s_addc_u32 s5, s85, 0
	v_mov_b32_e32 v2, 0x1000
	v_mov_b32_e32 v4, 1
	global_atomic_add v4, v2, v4, s[4:5] offset:1024 sc0
	v_cvt_f32_u32_e32 v2, v3
	v_sub_u32_e32 v5, 0, v3
	v_rcp_iflag_f32_e32 v2, v2
	s_nop 0
	v_mul_f32_e32 v2, 0x4f7ffffe, v2
	v_cvt_u32_f32_e32 v2, v2
	v_mul_lo_u32 v5, v5, v2
	v_mul_hi_u32 v5, v2, v5
	v_add_u32_e32 v2, v2, v5
	s_waitcnt vmcnt(0)
	v_mul_hi_u32 v2, v4, v2
	v_mul_lo_u32 v5, v2, v3
	v_sub_u32_e32 v5, v4, v5
	v_add_u32_e32 v6, 1, v2
	v_cmp_ge_u32_e32 vcc, v5, v3
	v_add_u32_e32 v4, 1, v4
	s_nop 0
	v_cndmask_b32_e32 v2, v2, v6, vcc
	v_sub_u32_e32 v6, v5, v3
	v_cndmask_b32_e32 v5, v5, v6, vcc
	v_add_u32_e32 v6, 1, v2
	v_cmp_ge_u32_e32 vcc, v5, v3
	s_nop 1
	v_cndmask_b32_e32 v2, v2, v6, vcc
	v_mul_lo_u32 v5, v3, v2
	v_add_u32_e32 v3, v5, v3
	v_cmp_ne_u32_e32 vcc, v4, v3
	s_and_saveexec_b64 s[2:3], vcc
	s_xor_b64 s[6:7], exec, s[2:3]
	s_cbranch_execz .LBB0_659
	s_waitcnt lgkmcnt(0)
	v_mov_b32_e32 v1, 0x2000
	global_load_dword v1, v1, s[4:5] offset:1024 sc1
	s_add_u32 s12, s4, 0x2400
	s_addc_u32 s13, s5, 0
	s_waitcnt vmcnt(0)
	v_cmp_eq_u32_e32 vcc, v1, v2
	s_and_saveexec_b64 s[8:9], vcc
	s_cbranch_execz .LBB0_658
	v_mov_b32_e32 v1, 0
	v_mov_b32_e32 v3, 0x1400
	s_mov_b32 s2, 0
	s_mov_b32 s3, 0
.Lb6l_8:
	s_sleep 1
	global_load_dword v16, v1, s[12:13] sc1
	s_cmp_lg_u32 s2, 0
	s_cbranch_scc1 .Lb6b_8
	global_load_dword v17, v3, s[4:5] offset:128 sc1
	s_waitcnt vmcnt(0)
	v_cmp_ne_u32_e32 vcc, v16, v2
	s_cbranch_vccnz .LBB0_658
	v_cmp_le_u32_e32 vcc, v17, v2
	s_cbranch_vccnz .Lb6c_8
	buffer_inv sc1
	s_mov_b32 s2, 1
	s_branch .Lb6c_8
.Lb6b_8:
	s_waitcnt vmcnt(0)
	v_cmp_ne_u32_e32 vcc, v16, v2
	s_cbranch_vccnz .Lb6done_8

.LBB0_659:
	s_andn2_saveexec_b64 s[2:3], s[6:7]
	s_cbranch_execz .LBB0_677
	s_mov_b64 s[6:7], exec
	buffer_wbl2 sc1
	s_waitcnt lgkmcnt(0)
	s_waitcnt vmcnt(0)
	v_mov_b32_e32 v3, 0x1400
	v_mov_b32_e32 v4, 1
	global_atomic_add v3, v4, s[4:5] offset:128
	v_mbcnt_lo_u32_b32 v2, s6, 0
	v_mbcnt_hi_u32_b32 v2, s7, v2
	v_cmp_eq_u32_e32 vcc, 0, v2
	s_and_saveexec_b64 s[8:9], vcc
	s_cbranch_execz .LBB0_662
	s_bcnt1_i32_b64 s2, s[6:7]
	v_mov_b32_e32 v3, 0x7000
	v_mov_b32_e32 v4, s2
	global_atomic_add v3, v3, v4, s[82:83] offset:1024 sc0

.Lb1spin_8:
	buffer_inv sc1
	v_mov_b32_e32 v1, 0
	global_load_dword v2, v1, s[8:9] sc1
	s_mov_b64 s[16:17], 0
	s_waitcnt vmcnt(0)
	v_cmp_eq_u32_e32 vcc, v2, v4
	s_and_saveexec_b64 s[12:13], vcc
	s_cbranch_execz .LBB0_673
	s_add_u32 s10, s82, 0x4200
	s_addc_u32 s11, s83, 0
	s_mov_b32 s2, 1
	s_branch .LBB0_666

.LBB0_676:
	s_or_b64 exec, exec, s[6:7]
	v_mov_b32_e32 v1, 0x2000
	v_mov_b32_e32 v2, 1
	s_waitcnt vmcnt(0)
	s_waitcnt vmcnt(0)

.Lb1spin_10:
	buffer_inv sc1
	v_mov_b32_e32 v1, 0
	global_load_dword v2, v1, s[8:9] sc1
	s_mov_b64 s[14:15], 0
	s_waitcnt vmcnt(0)
	v_cmp_eq_u32_e32 vcc, v2, v4
	s_and_saveexec_b64 s[12:13], vcc
	s_cbranch_execz .LBB0_881
	s_add_u32 s10, s82, 0x4200
	s_addc_u32 s11, s83, 0
	s_mov_b32 s2, 1
	s_branch .LBB0_874
